# plus P1 epilogue: row statistics prefetched at unit start, counted vmcnt(8) instead of full drain
# speedup vs baseline: 1.0031x; 1.0031x over previous
;     __device__ __forceinline__ void operator()(const f32x4 (&acc)[2][2][4][2], const Unit& u, int wr, int wc, int fr, int fq) const {
;     ...
;             for (int m = 0; m < 4; ++m) rsv[ai][m] = rowss[row0 + ai * HALF + m * 16];
; template <class Epi, class Sched, bool ALIGN_EPI = false, bool SP2 = false>
; __device__ __forceinline__ void gemm_phase(PG8_LAS unsigned char* lds, const Gemm g, const Sched& S, const Epi& E) {
;     ...
;     f32x4 acc[2][2][4][2];
; #pragma unroll
;     for (int a = 0; a < 2; ++a)
; #pragma unroll
;         for (int b = 0; b < 2; ++b)
; #pragma unroll
;             for (int m = 0; m < 4; ++m)
; #pragma unroll
;                 for (int n = 0; n < 2; ++n) acc[a][b][m][n] = (f32x4){0.f, 0.f, 0.f, 0.f};
;     bf16x8 At[4][2], B0[2][2], B1[2][2];
;     const char* cA = (const char*)g.A + (size_t)cur.br * g.abr + (size_t)cur.pm * tstep; const char* cB = (const char*)g.Bt + (size_t)cur.br * g.bbr + (size_t)cur.pn * tstep;
.LBB0_134:
	v_lshl_add_u32 v250, s57, 8, v154
	v_ashrrev_i32_e32 v251, 31, v250
	v_lshl_add_u64 v[250:251], v[250:251], 2, s[10:11]
	global_load_dword v241, v[250:251], off
	global_load_dword v242, v[250:251], off offset:64
	global_load_dword v243, v[250:251], off offset:128
	global_load_dword v244, v[250:251], off offset:192
	global_load_dword v245, v[250:251], off offset:512
	global_load_dword v246, v[250:251], off offset:576
	global_load_dword v247, v[250:251], off offset:640
	global_load_dword v248, v[250:251], off offset:704
	s_ashr_i32 s23, s22, 31
	s_lshl_b64 s[12:13], s[22:23], 19
	s_add_u32 s24, s14, s12
	s_addc_u32 s25, s15, s13
	s_and_b64 s[12:13], s[4:5], exec
	s_cselect_b32 s12, s25, s29
	s_cselect_b32 s13, s24, s28
	s_ashr_i32 s21, s20, 31
	s_lshl_b64 s[26:27], s[20:21], 19
	s_add_u32 s26, s17, s26
	s_addc_u32 s27, s38, s27
	s_and_b64 s[42:43], s[4:5], exec
	s_cselect_b32 s21, s27, s31
	s_cselect_b32 s23, s26, s30
	s_add_u32 s28, s28, 0x40080
	s_addc_u32 s29, s29, 0
	s_add_u32 s58, s30, 0x100
	v_mov_b32_e32 v0, 0
	s_addc_u32 s60, s31, 0
	s_mov_b32 s61, -2
	v_mov_b32_e32 v1, v0
	v_mov_b32_e32 v2, v0
	v_mov_b32_e32 v3, v0
	v_mov_b32_e32 v4, v0
	v_mov_b32_e32 v5, v0
	v_mov_b32_e32 v6, v0
	v_mov_b32_e32 v7, v0
	v_mov_b32_e32 v16, v0
	v_mov_b32_e32 v17, v0
	v_mov_b32_e32 v18, v0
	v_mov_b32_e32 v19, v0
	v_mov_b32_e32 v20, v0
	v_mov_b32_e32 v21, v0
	v_mov_b32_e32 v22, v0
	v_mov_b32_e32 v23, v0
	v_mov_b32_e32 v32, v0
	v_mov_b32_e32 v33, v0
	v_mov_b32_e32 v34, v0
	v_mov_b32_e32 v35, v0
	v_mov_b32_e32 v36, v0
	v_mov_b32_e32 v37, v0
	v_mov_b32_e32 v38, v0
	v_mov_b32_e32 v39, v0
	v_mov_b32_e32 v48, v0
	v_mov_b32_e32 v49, v0
	v_mov_b32_e32 v50, v0
	v_mov_b32_e32 v51, v0
	v_mov_b32_e32 v52, v0
	v_mov_b32_e32 v53, v0
	v_mov_b32_e32 v54, v0
	v_mov_b32_e32 v55, v0
	v_mov_b32_e32 v8, v0
	v_mov_b32_e32 v9, v0
	v_mov_b32_e32 v10, v0
	v_mov_b32_e32 v11, v0
	v_mov_b32_e32 v12, v0
	v_mov_b32_e32 v13, v0
	v_mov_b32_e32 v14, v0
	v_mov_b32_e32 v15, v0
	v_mov_b32_e32 v24, v0
	v_mov_b32_e32 v25, v0
	v_mov_b32_e32 v26, v0
	v_mov_b32_e32 v27, v0
	v_mov_b32_e32 v28, v0
	v_mov_b32_e32 v29, v0
	v_mov_b32_e32 v30, v0
	v_mov_b32_e32 v31, v0
	v_mov_b32_e32 v40, v0
	v_mov_b32_e32 v41, v0
	v_mov_b32_e32 v42, v0
	v_mov_b32_e32 v43, v0
	v_mov_b32_e32 v44, v0
	v_mov_b32_e32 v45, v0
	v_mov_b32_e32 v46, v0
	v_mov_b32_e32 v47, v0
	v_mov_b32_e32 v56, v0
	v_mov_b32_e32 v57, v0
	v_mov_b32_e32 v58, v0
	v_mov_b32_e32 v59, v0
	v_mov_b32_e32 v60, v0
	v_mov_b32_e32 v61, v0
	v_mov_b32_e32 v62, v0
	v_mov_b32_e32 v63, v0
	v_mov_b32_e32 v64, v0
	v_mov_b32_e32 v65, v0
	v_mov_b32_e32 v66, v0
	v_mov_b32_e32 v67, v0
	v_mov_b32_e32 v68, v0
	v_mov_b32_e32 v69, v0
	v_mov_b32_e32 v70, v0
	v_mov_b32_e32 v71, v0
	v_mov_b32_e32 v80, v0
	v_mov_b32_e32 v81, v0
	v_mov_b32_e32 v82, v0
	v_mov_b32_e32 v83, v0
	v_mov_b32_e32 v84, v0
	v_mov_b32_e32 v85, v0
	v_mov_b32_e32 v86, v0
	v_mov_b32_e32 v87, v0
	v_mov_b32_e32 v96, v0
	v_mov_b32_e32 v97, v0
	v_mov_b32_e32 v98, v0
	v_mov_b32_e32 v99, v0
	v_mov_b32_e32 v100, v0
	v_mov_b32_e32 v101, v0
	v_mov_b32_e32 v102, v0
	v_mov_b32_e32 v103, v0
	v_mov_b32_e32 v112, v0
	v_mov_b32_e32 v113, v0
	v_mov_b32_e32 v114, v0
	v_mov_b32_e32 v115, v0
	v_mov_b32_e32 v116, v0
	v_mov_b32_e32 v117, v0
	v_mov_b32_e32 v118, v0
	v_mov_b32_e32 v119, v0
	v_mov_b32_e32 v72, v0
	v_mov_b32_e32 v73, v0
	v_mov_b32_e32 v74, v0
	v_mov_b32_e32 v75, v0
	v_mov_b32_e32 v76, v0
	v_mov_b32_e32 v77, v0
	v_mov_b32_e32 v78, v0
	v_mov_b32_e32 v79, v0
	v_mov_b32_e32 v88, v0
	v_mov_b32_e32 v89, v0
	v_mov_b32_e32 v90, v0
	v_mov_b32_e32 v91, v0
	v_mov_b32_e32 v92, v0
	v_mov_b32_e32 v93, v0
	v_mov_b32_e32 v94, v0
	v_mov_b32_e32 v95, v0
	v_mov_b32_e32 v104, v0
	v_mov_b32_e32 v105, v0
	v_mov_b32_e32 v106, v0
	v_mov_b32_e32 v107, v0
	v_mov_b32_e32 v108, v0
	v_mov_b32_e32 v109, v0
	v_mov_b32_e32 v110, v0
	v_mov_b32_e32 v111, v0
	v_mov_b32_e32 v120, v0
	v_mov_b32_e32 v121, v0
	v_mov_b32_e32 v122, v0
	v_mov_b32_e32 v123, v0
	v_mov_b32_e32 v124, v0
	v_mov_b32_e32 v125, v0
	v_mov_b32_e32 v126, v0
	v_mov_b32_e32 v127, v0

; __device__ __forceinline__ unsigned cvt_pk_bf16(float lo, float hi) { unsigned r; asm volatile("v_cvt_pk_bf16_f32 %0, %1, %2" : "=v"(r) : "v"(lo), "v"(hi)); return r; }
;     __device__ __forceinline__ void operator()(const f32x4 (&acc)[2][2][4][2], const Unit& u, int wr, int wc, int fr, int fq) const {
;         const int row0 = u.pm * BM + wr * 64 + fr, col0 = u.pn * BM + wc * 32 + 8 * fq, pn = u.pn;
;         const float sc = (pn < 6 || (pn >= 20 && pn < 22) || (pn >= 25 && pn < 27)) ? 0.125f * 1.4426950408889634f : 1.0f;
;         float rsv[2][4];
; #pragma unroll
;         for (int ai = 0; ai < 2; ++ai)
; #pragma unroll
;             for (int m = 0; m < 4; ++m) rsv[ai][m] = rowss[row0 + ai * HALF + m * 16];
; #pragma unroll
;         for (int ai = 0; ai < 2; ++ai)
; #pragma unroll
;             for (int m = 0; m < 4; ++m) { const int row = row0 + ai * HALF + m * 16; const float rs = rsqrtf(rsv[ai][m] * (1.0f / 1024.0f) + 1e-6f) * sc;
; #pragma unroll
;                 for (int bj = 0; bj < 2; ++bj) { const f32x4 v0 = acc[ai][bj][m][0] * rs, v1 = acc[ai][bj][m][1] * rs;
;                     u32x4 w; w.x = cvt_pk_bf16(v0[0], v0[1]); w.y = cvt_pk_bf16(v0[2], v0[3]); w.z = cvt_pk_bf16(v1[0], v1[1]); w.w = cvt_pk_bf16(v1[2], v1[3]);
;                     *(u32x4*)(O + PB(col0 + bj * HALF) + (size_t)row * 64) = w; } }
.LBB0_138:
	v_lshl_add_u32 v140, s57, 8, v154
	v_ashrrev_i32_e32 v141, 31, v140
	s_cmp_lt_i32 s46, 6
	s_cselect_b64 s[12:13], -1, 0
	s_and_b32 s21, s46, 0x7ffffffe
	s_cmp_eq_u32 s21, 20
	s_cselect_b64 s[28:29], -1, 0
	s_or_b64 s[12:13], s[12:13], s[28:29]
	s_sub_i32 s21, s46, 25
	s_cmp_lt_u32 s21, 2
	s_cselect_b64 s[28:29], -1, 0
	s_or_b64 vcc, s[12:13], s[28:29]
	v_cndmask_b32_e32 v157, 1.0, v237, vcc
	v_lshlrev_b64 v[166:167], 7, v[140:141]
	s_mov_b64 s[12:13], 0x4000
	v_lshl_add_u64 v[146:147], v[166:167], 0, s[12:13]
	s_mov_b64 s[12:13], 0x4800
	v_lshl_add_u64 v[144:145], v[166:167], 0, s[12:13]
	s_mov_b64 s[12:13], 0x5000
	v_lshl_add_u64 v[142:143], v[166:167], 0, s[12:13]
	s_mov_b64 s[12:13], 0x5800
	v_or_b32_e32 v152, 16, v140
	v_or_b32_e32 v150, 32, v140
	v_or_b32_e32 v148, 48, v140
	v_lshl_add_u64 v[140:141], v[166:167], 0, s[12:13]
	s_lshl_b32 s12, s46, 8
	s_or_b32 s12, s12, s49
	s_ashr_i32 s12, s12, 6
	s_ashr_i32 s13, s12, 31
	s_lshl_b64 s[28:29], s[12:13], 21
	s_or_b32 s12, s12, 2
	s_ashr_i32 s13, s12, 31
	s_lshl_b64 s[12:13], s[12:13], 21
	v_ashrrev_i32_e32 v153, 31, v152
	v_ashrrev_i32_e32 v151, 31, v150
	v_ashrrev_i32_e32 v149, 31, v148
	s_waitcnt vmcnt(8)
	v_fmamk_f32 v164, v241, 0x3a800000, v230
	v_cmp_gt_f32_e32 vcc, s37, v164
	v_mul_f32_e32 v165, 0x4b800000, v164
	s_nop 0
	v_cndmask_b32_e32 v164, v164, v165, vcc
	v_rsq_f32_e32 v164, v164
	s_nop 0
	v_mul_f32_e32 v165, 0x45800000, v164
	v_cndmask_b32_e32 v164, v164, v165, vcc
	v_mul_f32_e32 v164, v157, v164
	v_pk_mul_f32 v[124:125], v[124:125], v[164:165] op_sel_hi:[1,0]
	v_pk_mul_f32 v[120:121], v[120:121], v[164:165] op_sel_hi:[1,0]
	v_pk_mul_f32 v[126:127], v[126:127], v[164:165] op_sel_hi:[1,0]
	v_pk_mul_f32 v[168:169], v[122:123], v[164:165] op_sel_hi:[1,0]
	v_cvt_pk_bf16_f32 v122, v124, v125
	v_cvt_pk_bf16_f32 v123, v126, v127
	v_cvt_pk_bf16_f32 v124, v120, v121
	v_lshl_add_u64 v[120:121], v[134:135], 0, s[28:29]
	v_lshl_add_u64 v[126:127], v[120:121], 0, v[166:167]
	v_pk_mul_f32 v[116:117], v[116:117], v[164:165] op_sel_hi:[1,0]
	v_pk_mul_f32 v[112:113], v[112:113], v[164:165] op_sel_hi:[1,0]
	v_cvt_pk_bf16_f32 v125, v168, v169
	global_store_dwordx4 v[126:127], v[122:125], off
	v_pk_mul_f32 v[118:119], v[118:119], v[164:165] op_sel_hi:[1,0]
	s_nop 0
	v_pk_mul_f32 v[122:123], v[114:115], v[164:165] op_sel_hi:[1,0]
	v_cvt_pk_bf16_f32 v114, v116, v117
	v_cvt_pk_bf16_f32 v115, v118, v119
	v_cvt_pk_bf16_f32 v116, v112, v113
	v_lshl_add_u64 v[112:113], v[134:135], 0, s[12:13]
	v_lshl_add_u64 v[118:119], v[112:113], 0, v[166:167]
	v_cvt_pk_bf16_f32 v117, v122, v123
	global_store_dwordx4 v[118:119], v[114:117], off
	s_mov_b64 s[12:13], -1
	s_nop 0
	v_fmamk_f32 v114, v242, 0x3a800000, v230
	v_cmp_gt_f32_e32 vcc, s37, v114
	v_mul_f32_e32 v115, 0x4b800000, v114
	v_lshlrev_b64 v[116:117], 7, v[152:153]
	v_cndmask_b32_e32 v114, v114, v115, vcc
	v_rsq_f32_e32 v114, v114
	s_nop 0
	v_mul_f32_e32 v115, 0x45800000, v114
	v_cndmask_b32_e32 v114, v114, v115, vcc
	v_mul_f32_e32 v114, v157, v114
	v_pk_mul_f32 v[108:109], v[108:109], v[114:115] op_sel_hi:[1,0]
	v_pk_mul_f32 v[110:111], v[110:111], v[114:115] op_sel_hi:[1,0]
	v_pk_mul_f32 v[118:119], v[106:107], v[114:115] op_sel_hi:[1,0]
	v_pk_mul_f32 v[106:107], v[104:105], v[114:115] op_sel_hi:[1,0]
	v_cvt_pk_bf16_f32 v104, v108, v109
	v_cvt_pk_bf16_f32 v105, v110, v111
	v_lshl_add_u64 v[108:109], v[120:121], 0, v[116:117]
	v_pk_mul_f32 v[100:101], v[100:101], v[114:115] op_sel_hi:[1,0]
	v_cvt_pk_bf16_f32 v106, v106, v107
	v_cvt_pk_bf16_f32 v107, v118, v119
	global_store_dwordx4 v[108:109], v[104:107], off
	v_pk_mul_f32 v[102:103], v[102:103], v[114:115] op_sel_hi:[1,0]
	s_nop 0
	v_pk_mul_f32 v[104:105], v[98:99], v[114:115] op_sel_hi:[1,0]
	v_pk_mul_f32 v[98:99], v[96:97], v[114:115] op_sel_hi:[1,0]
	v_cvt_pk_bf16_f32 v96, v100, v101
	v_lshl_add_u64 v[100:101], v[112:113], 0, v[116:117]
	v_cvt_pk_bf16_f32 v97, v102, v103
	v_cvt_pk_bf16_f32 v98, v98, v99
	v_cvt_pk_bf16_f32 v99, v104, v105
	global_store_dwordx4 v[100:101], v[96:99], off
	s_nop 1
	v_fmamk_f32 v96, v243, 0x3a800000, v230
	v_cmp_gt_f32_e32 vcc, s37, v96
	v_mul_f32_e32 v97, 0x4b800000, v96
	v_lshlrev_b64 v[98:99], 7, v[150:151]
	v_cndmask_b32_e32 v96, v96, v97, vcc
	v_rsq_f32_e32 v96, v96
	s_nop 0
	v_mul_f32_e32 v97, 0x45800000, v96
	v_cndmask_b32_e32 v96, v96, v97, vcc
	v_mul_f32_e32 v96, v157, v96
	v_pk_mul_f32 v[92:93], v[92:93], v[96:97] op_sel_hi:[1,0]
	v_pk_mul_f32 v[94:95], v[94:95], v[96:97] op_sel_hi:[1,0]
	v_pk_mul_f32 v[100:101], v[90:91], v[96:97] op_sel_hi:[1,0]
	v_pk_mul_f32 v[90:91], v[88:89], v[96:97] op_sel_hi:[1,0]
	v_cvt_pk_bf16_f32 v88, v92, v93
	v_cvt_pk_bf16_f32 v89, v94, v95
	v_lshl_add_u64 v[92:93], v[120:121], 0, v[98:99]
	v_pk_mul_f32 v[84:85], v[84:85], v[96:97] op_sel_hi:[1,0]
	v_cvt_pk_bf16_f32 v90, v90, v91
	v_cvt_pk_bf16_f32 v91, v100, v101
	global_store_dwordx4 v[92:93], v[88:91], off
	v_pk_mul_f32 v[86:87], v[86:87], v[96:97] op_sel_hi:[1,0]
	s_nop 0
	v_pk_mul_f32 v[88:89], v[82:83], v[96:97] op_sel_hi:[1,0]
	v_pk_mul_f32 v[82:83], v[80:81], v[96:97] op_sel_hi:[1,0]
	v_cvt_pk_bf16_f32 v80, v84, v85
	v_lshl_add_u64 v[84:85], v[112:113], 0, v[98:99]
	v_cvt_pk_bf16_f32 v81, v86, v87
	v_cvt_pk_bf16_f32 v82, v82, v83
	v_cvt_pk_bf16_f32 v83, v88, v89
	global_store_dwordx4 v[84:85], v[80:83], off
	s_nop 1
	v_fmamk_f32 v80, v244, 0x3a800000, v230
	v_cmp_gt_f32_e32 vcc, s37, v80
	v_mul_f32_e32 v81, 0x4b800000, v80
	v_lshlrev_b64 v[82:83], 7, v[148:149]
	v_cndmask_b32_e32 v80, v80, v81, vcc
	v_rsq_f32_e32 v80, v80
	s_nop 0
	v_mul_f32_e32 v81, 0x45800000, v80
	v_cndmask_b32_e32 v80, v80, v81, vcc
	v_mul_f32_e32 v80, v157, v80
; __device__ __forceinline__ unsigned cvt_pk_bf16(float lo, float hi) { unsigned r; asm volatile("v_cvt_pk_bf16_f32 %0, %1, %2" : "=v"(r) : "v"(lo), "v"(hi)); return r; }
;     __device__ __forceinline__ void operator()(const f32x4 (&acc)[2][2][4][2], const Unit& u, int wr, int wc, int fr, int fq) const {
;     ...
;             for (int m = 0; m < 4; ++m) { const int row = row0 + ai * HALF + m * 16; const float rs = rsqrtf(rsv[ai][m] * (1.0f / 1024.0f) + 1e-6f) * sc;
; #pragma unroll
;                 for (int bj = 0; bj < 2; ++bj) { const f32x4 v0 = acc[ai][bj][m][0] * rs, v1 = acc[ai][bj][m][1] * rs;
;                     u32x4 w; w.x = cvt_pk_bf16(v0[0], v0[1]); w.y = cvt_pk_bf16(v0[2], v0[3]); w.z = cvt_pk_bf16(v1[0], v1[1]); w.w = cvt_pk_bf16(v1[2], v1[3]);
;                     *(u32x4*)(O + PB(col0 + bj * HALF) + (size_t)row * 64) = w; } }
; template <class Epi, class Sched, bool ALIGN_EPI = false, bool SP2 = false>
; __device__ __forceinline__ void gemm_phase(PG8_LAS unsigned char* lds, const Gemm g, const Sched& S, const Epi& E) {
;     ...
;         if (!has_next) break;
	v_pk_mul_f32 v[76:77], v[76:77], v[80:81] op_sel_hi:[1,0]
	v_pk_mul_f32 v[78:79], v[78:79], v[80:81] op_sel_hi:[1,0]
	v_pk_mul_f32 v[84:85], v[74:75], v[80:81] op_sel_hi:[1,0]
	v_pk_mul_f32 v[74:75], v[72:73], v[80:81] op_sel_hi:[1,0]
	v_cvt_pk_bf16_f32 v72, v76, v77
	v_cvt_pk_bf16_f32 v73, v78, v79
	v_lshl_add_u64 v[76:77], v[120:121], 0, v[82:83]
	v_pk_mul_f32 v[68:69], v[68:69], v[80:81] op_sel_hi:[1,0]
	v_cvt_pk_bf16_f32 v74, v74, v75
	v_cvt_pk_bf16_f32 v75, v84, v85
	global_store_dwordx4 v[76:77], v[72:75], off
	v_pk_mul_f32 v[70:71], v[70:71], v[80:81] op_sel_hi:[1,0]
	s_nop 0
	v_pk_mul_f32 v[72:73], v[66:67], v[80:81] op_sel_hi:[1,0]
	v_pk_mul_f32 v[66:67], v[64:65], v[80:81] op_sel_hi:[1,0]
	v_cvt_pk_bf16_f32 v64, v68, v69
	v_lshl_add_u64 v[68:69], v[112:113], 0, v[82:83]
	v_cvt_pk_bf16_f32 v65, v70, v71
	v_cvt_pk_bf16_f32 v66, v66, v67
	v_cvt_pk_bf16_f32 v67, v72, v73
	global_store_dwordx4 v[68:69], v[64:67], off
	s_nop 1
	v_fmamk_f32 v64, v245, 0x3a800000, v230
	v_cmp_gt_f32_e32 vcc, s37, v64
	v_mul_f32_e32 v65, 0x4b800000, v64
	s_nop 0
	v_cndmask_b32_e32 v64, v64, v65, vcc
	v_rsq_f32_e32 v64, v64
	s_nop 0
	v_mul_f32_e32 v65, 0x45800000, v64
	v_cndmask_b32_e32 v64, v64, v65, vcc
	v_mul_f32_e32 v64, v157, v64
	v_pk_mul_f32 v[60:61], v[60:61], v[64:65] op_sel_hi:[1,0]
	v_pk_mul_f32 v[62:63], v[62:63], v[64:65] op_sel_hi:[1,0]
	v_pk_mul_f32 v[66:67], v[58:59], v[64:65] op_sel_hi:[1,0]
	v_pk_mul_f32 v[58:59], v[56:57], v[64:65] op_sel_hi:[1,0]
	v_cvt_pk_bf16_f32 v56, v60, v61
	v_cvt_pk_bf16_f32 v57, v62, v63
	v_lshl_add_u64 v[60:61], v[120:121], 0, v[146:147]
	v_pk_mul_f32 v[52:53], v[52:53], v[64:65] op_sel_hi:[1,0]
	v_cvt_pk_bf16_f32 v58, v58, v59
	v_cvt_pk_bf16_f32 v59, v66, v67
	global_store_dwordx4 v[60:61], v[56:59], off
	v_pk_mul_f32 v[54:55], v[54:55], v[64:65] op_sel_hi:[1,0]
	s_nop 0
	v_pk_mul_f32 v[56:57], v[50:51], v[64:65] op_sel_hi:[1,0]
	v_pk_mul_f32 v[50:51], v[48:49], v[64:65] op_sel_hi:[1,0]
	v_cvt_pk_bf16_f32 v48, v52, v53
	v_lshl_add_u64 v[52:53], v[112:113], 0, v[146:147]
	v_cvt_pk_bf16_f32 v49, v54, v55
	v_cvt_pk_bf16_f32 v50, v50, v51
	v_cvt_pk_bf16_f32 v51, v56, v57
	global_store_dwordx4 v[52:53], v[48:51], off
	s_nop 1
	v_fmamk_f32 v48, v246, 0x3a800000, v230
	v_cmp_gt_f32_e32 vcc, s37, v48
	v_mul_f32_e32 v49, 0x4b800000, v48
	s_nop 0
	v_cndmask_b32_e32 v48, v48, v49, vcc
	v_rsq_f32_e32 v48, v48
	s_nop 0
	v_mul_f32_e32 v49, 0x45800000, v48
	v_cndmask_b32_e32 v48, v48, v49, vcc
	v_mul_f32_e32 v48, v157, v48
	v_pk_mul_f32 v[44:45], v[44:45], v[48:49] op_sel_hi:[1,0]
	v_pk_mul_f32 v[46:47], v[46:47], v[48:49] op_sel_hi:[1,0]
	v_pk_mul_f32 v[50:51], v[42:43], v[48:49] op_sel_hi:[1,0]
	v_pk_mul_f32 v[42:43], v[40:41], v[48:49] op_sel_hi:[1,0]
	v_cvt_pk_bf16_f32 v40, v44, v45
	v_cvt_pk_bf16_f32 v41, v46, v47
	v_lshl_add_u64 v[44:45], v[120:121], 0, v[144:145]
	v_pk_mul_f32 v[36:37], v[36:37], v[48:49] op_sel_hi:[1,0]
	v_cvt_pk_bf16_f32 v42, v42, v43
	v_cvt_pk_bf16_f32 v43, v50, v51
	global_store_dwordx4 v[44:45], v[40:43], off
	v_pk_mul_f32 v[38:39], v[38:39], v[48:49] op_sel_hi:[1,0]
	s_nop 0
	v_pk_mul_f32 v[40:41], v[34:35], v[48:49] op_sel_hi:[1,0]
	v_pk_mul_f32 v[34:35], v[32:33], v[48:49] op_sel_hi:[1,0]
	v_cvt_pk_bf16_f32 v32, v36, v37
	v_lshl_add_u64 v[36:37], v[112:113], 0, v[144:145]
	v_cvt_pk_bf16_f32 v33, v38, v39
	v_cvt_pk_bf16_f32 v34, v34, v35
	v_cvt_pk_bf16_f32 v35, v40, v41
	global_store_dwordx4 v[36:37], v[32:35], off
	s_nop 1
	v_fmamk_f32 v32, v247, 0x3a800000, v230
	v_cmp_gt_f32_e32 vcc, s37, v32
	v_mul_f32_e32 v33, 0x4b800000, v32
	s_nop 0
	v_cndmask_b32_e32 v32, v32, v33, vcc
	v_rsq_f32_e32 v32, v32
	s_nop 0
	v_mul_f32_e32 v33, 0x45800000, v32
	v_cndmask_b32_e32 v32, v32, v33, vcc
	v_mul_f32_e32 v32, v157, v32
	v_pk_mul_f32 v[28:29], v[28:29], v[32:33] op_sel_hi:[1,0]
	v_pk_mul_f32 v[30:31], v[30:31], v[32:33] op_sel_hi:[1,0]
	v_pk_mul_f32 v[34:35], v[26:27], v[32:33] op_sel_hi:[1,0]
	v_pk_mul_f32 v[26:27], v[24:25], v[32:33] op_sel_hi:[1,0]
	v_cvt_pk_bf16_f32 v24, v28, v29
	v_cvt_pk_bf16_f32 v25, v30, v31
	v_lshl_add_u64 v[28:29], v[120:121], 0, v[142:143]
	v_pk_mul_f32 v[20:21], v[20:21], v[32:33] op_sel_hi:[1,0]
	v_cvt_pk_bf16_f32 v26, v26, v27
	v_cvt_pk_bf16_f32 v27, v34, v35
	global_store_dwordx4 v[28:29], v[24:27], off
	v_pk_mul_f32 v[22:23], v[22:23], v[32:33] op_sel_hi:[1,0]
	s_nop 0
	v_pk_mul_f32 v[24:25], v[18:19], v[32:33] op_sel_hi:[1,0]
	v_pk_mul_f32 v[18:19], v[16:17], v[32:33] op_sel_hi:[1,0]
	v_cvt_pk_bf16_f32 v16, v20, v21
	v_lshl_add_u64 v[20:21], v[112:113], 0, v[142:143]
	v_cvt_pk_bf16_f32 v17, v22, v23
	v_cvt_pk_bf16_f32 v18, v18, v19
	v_cvt_pk_bf16_f32 v19, v24, v25
	global_store_dwordx4 v[20:21], v[16:19], off
	s_nop 1
	v_fmamk_f32 v16, v248, 0x3a800000, v230
	v_cmp_gt_f32_e32 vcc, s37, v16
	v_mul_f32_e32 v17, 0x4b800000, v16
	s_nop 0
	v_cndmask_b32_e32 v16, v16, v17, vcc
	v_rsq_f32_e32 v16, v16
	s_nop 0
	v_mul_f32_e32 v17, 0x45800000, v16
	v_cndmask_b32_e32 v16, v16, v17, vcc
	v_mul_f32_e32 v16, v157, v16
	v_pk_mul_f32 v[12:13], v[12:13], v[16:17] op_sel_hi:[1,0]
	v_pk_mul_f32 v[14:15], v[14:15], v[16:17] op_sel_hi:[1,0]
	v_pk_mul_f32 v[18:19], v[10:11], v[16:17] op_sel_hi:[1,0]
	v_pk_mul_f32 v[10:11], v[8:9], v[16:17] op_sel_hi:[1,0]
	v_cvt_pk_bf16_f32 v8, v12, v13
	v_cvt_pk_bf16_f32 v9, v14, v15
	v_lshl_add_u64 v[12:13], v[120:121], 0, v[140:141]
	v_pk_mul_f32 v[4:5], v[4:5], v[16:17] op_sel_hi:[1,0]
	v_cvt_pk_bf16_f32 v10, v10, v11
	v_cvt_pk_bf16_f32 v11, v18, v19
	global_store_dwordx4 v[12:13], v[8:11], off
	s_andn2_b64 vcc, exec, s[4:5]
	v_pk_mul_f32 v[6:7], v[6:7], v[16:17] op_sel_hi:[1,0]
	v_pk_mul_f32 v[8:9], v[2:3], v[16:17] op_sel_hi:[1,0]
	v_pk_mul_f32 v[2:3], v[0:1], v[16:17] op_sel_hi:[1,0]
	v_cvt_pk_bf16_f32 v0, v4, v5
	v_lshl_add_u64 v[4:5], v[112:113], 0, v[140:141]
	v_cvt_pk_bf16_f32 v1, v6, v7
	v_cvt_pk_bf16_f32 v2, v2, v3
	v_cvt_pk_bf16_f32 v3, v8, v9
	global_store_dwordx4 v[4:5], v[0:3], off
	s_cbranch_vccnz .LBB0_131
	s_andn2_b64 vcc, exec, s[8:9]
	s_cbranch_vccnz .LBB0_130
	s_barrier
	s_branch .LBB0_130
